# scan<2> scanner loop rewritten by hand (42 instr/step instead of 62) + hazard nops in scan<4> chunk prologue
# speedup vs baseline: 1.0005x; 1.0005x over previous
.LBB0_412:
	s_and_b32 s2, s6, 1
	s_mul_i32 s3, s2, 0xc000
	s_lshl_b32 s2, s2, 13
	s_add_i32 s2, s2, 0x18000
	v_lshl_add_u32 v107, v101, 4, s3
	v_lshl_add_u32 v106, v100, 2, s3
	v_add_u32_e32 v105, s2, v102
	ds_read_b128 v[0:3], v107 offset:0
	ds_read_b128 v[4:7], v107 offset:16
	ds_read_b128 v[8:11], v107 offset:256
	ds_read_b128 v[12:15], v107 offset:272
	ds_read_b128 v[24:27], v107 offset:768
	ds_read_b128 v[28:31], v107 offset:784
	ds_read_b64 v[40:41], v106 offset:1280
	ds_read_b128 v[16:19], v107 offset:512
	ds_read_b128 v[20:23], v107 offset:528
	ds_read_b128 v[32:35], v107 offset:1024
	ds_read_b128 v[36:39], v107 offset:1040
	s_mov_b32 s7, 32
	s_waitcnt lgkmcnt(9)
	v_pk_mul_f32 v[108:109], v[82:83], v[0:1] op_sel_hi:[1,0]
	s_nop 0
	v_pk_fma_f32 v[108:109], v[84:85], v[0:1], v[108:109] op_sel:[0,1,0]
	s_nop 0
	v_pk_fma_f32 v[108:109], v[86:87], v[2:3], v[108:109] op_sel_hi:[1,0,1]
	s_nop 0
	v_pk_fma_f32 v[108:109], v[88:89], v[2:3], v[108:109] op_sel:[0,1,0]
	s_nop 0
	v_pk_fma_f32 v[108:109], v[90:91], v[4:5], v[108:109] op_sel_hi:[1,0,1]
	s_nop 0
	v_pk_fma_f32 v[108:109], v[92:93], v[4:5], v[108:109] op_sel:[0,1,0]
	s_nop 0
	v_pk_fma_f32 v[108:109], v[94:95], v[6:7], v[108:109] op_sel_hi:[1,0,1]
	s_nop 0
	v_pk_fma_f32 v[108:109], v[96:97], v[6:7], v[108:109] op_sel:[0,1,0]
	ds_read_b128 v[42:45], v107 offset:1536
	ds_read_b128 v[46:49], v107 offset:1552
	ds_read_b128 v[50:53], v107 offset:1792
	ds_read_b128 v[54:57], v107 offset:1808
	ds_read_b128 v[66:69], v107 offset:2304
	ds_read_b128 v[70:73], v107 offset:2320
	ds_read_b64 v[98:99], v106 offset:2816
	ds_read_b128 v[58:61], v107 offset:2048
	ds_read_b128 v[62:65], v107 offset:2064
	ds_read_b128 v[74:77], v107 offset:2560
	ds_read_b128 v[78:81], v107 offset:2576
	v_add_f32_dpp v108, v108, v108 quad_perm:[1,0,3,2] row_mask:0xf bank_mask:0xf bound_ctrl:1
	v_add_f32_dpp v109, v109, v109 quad_perm:[1,0,3,2] row_mask:0xf bank_mask:0xf bound_ctrl:1
	s_nop 0
	v_add_f32_dpp v108, v108, v108 quad_perm:[2,3,0,1] row_mask:0xf bank_mask:0xf bound_ctrl:1
	v_add_f32_dpp v109, v109, v109 quad_perm:[2,3,0,1] row_mask:0xf bank_mask:0xf bound_ctrl:1
	s_nop 0
	v_add_f32_dpp v108, v108, v108 row_half_mirror row_mask:0xf bank_mask:0xf bound_ctrl:1
	v_add_f32_dpp v109, v109, v109 row_half_mirror row_mask:0xf bank_mask:0xf bound_ctrl:1

.LBB0_470:
	s_and_b32 s2, s6, 1
	s_mul_i32 s3, s2, 0xc000
	s_lshl_b32 s2, s2, 13
	s_add_i32 s2, s2, 0x18000
	v_lshl_add_u32 v97, v93, 4, s3
	v_lshl_add_u32 v102, v92, 2, s3
	v_add_u32_e32 v89, s2, v94
	ds_read_b128 v[0:3], v97 offset:0
	ds_read_b128 v[4:7], v97 offset:16
	ds_read_b128 v[8:11], v97 offset:256
	ds_read_b128 v[12:15], v97 offset:272
	ds_read_b128 v[24:27], v97 offset:768
	ds_read_b128 v[28:31], v97 offset:784
	ds_read_b32 v88, v102 offset:1280
	ds_read_b128 v[16:19], v97 offset:512
	ds_read_b128 v[20:23], v97 offset:528
	ds_read_b128 v[32:35], v97 offset:1024
	ds_read_b128 v[36:39], v97 offset:1040
	s_mov_b32 s7, 32
	s_waitcnt lgkmcnt(9)
	v_pk_mul_f32 v[98:99], v[80:81], v[0:1]
	s_nop 0
	v_pk_fma_f32 v[98:99], v[82:83], v[2:3], v[98:99]
	s_nop 0
	v_pk_fma_f32 v[98:99], v[84:85], v[4:5], v[98:99]
	s_nop 0
	v_pk_fma_f32 v[98:99], v[86:87], v[6:7], v[98:99]
	s_nop 0
	v_add_f32_e32 v98, v98, v99
	ds_read_b128 v[40:43], v97 offset:1536
	ds_read_b128 v[44:47], v97 offset:1552
	ds_read_b128 v[48:51], v97 offset:1792
	ds_read_b128 v[52:55], v97 offset:1808
	ds_read_b128 v[64:67], v97 offset:2304
	ds_read_b128 v[68:71], v97 offset:2320
	ds_read_b32 v90, v102 offset:2816
	ds_read_b128 v[56:59], v97 offset:2048
	ds_read_b128 v[60:63], v97 offset:2064
	ds_read_b128 v[72:75], v97 offset:2560
	ds_read_b128 v[76:79], v97 offset:2576
	v_add_f32_dpp v98, v98, v98 quad_perm:[1,0,3,2] row_mask:0xf bank_mask:0xf bound_ctrl:1
	s_nop 1
	v_add_f32_dpp v98, v98, v98 quad_perm:[2,3,0,1] row_mask:0xf bank_mask:0xf bound_ctrl:1
	s_nop 1
	v_add_f32_dpp v98, v98, v98 row_half_mirror row_mask:0xf bank_mask:0xf bound_ctrl:1
.Lscnh_loop:
	s_waitcnt lgkmcnt(11)
	v_pk_mul_f32 v[80:81], v[80:81], v[8:9]
	v_pk_mul_f32 v[82:83], v[82:83], v[10:11]
	v_pk_mul_f32 v[84:85], v[84:85], v[12:13]
	v_pk_mul_f32 v[86:87], v[86:87], v[14:15]
	v_pk_fma_f32 v[80:81], v[88:89], v[24:25], v[80:81] op_sel_hi:[0,1,1]
	v_pk_fma_f32 v[82:83], v[88:89], v[26:27], v[82:83] op_sel_hi:[0,1,1]
	v_pk_fma_f32 v[84:85], v[88:89], v[28:29], v[84:85] op_sel_hi:[0,1,1]
	v_pk_fma_f32 v[86:87], v[88:89], v[30:31], v[86:87] op_sel_hi:[0,1,1]
	v_pk_fma_f32 v[80:81], v[98:99], v[16:17], v[80:81] op_sel_hi:[0,1,1]
	v_pk_fma_f32 v[82:83], v[98:99], v[18:19], v[82:83] op_sel_hi:[0,1,1]
	v_pk_fma_f32 v[84:85], v[98:99], v[20:21], v[84:85] op_sel_hi:[0,1,1]
	v_pk_fma_f32 v[86:87], v[98:99], v[22:23], v[86:87] op_sel_hi:[0,1,1]
	s_waitcnt lgkmcnt(9)
	v_pk_mul_f32 v[98:99], v[80:81], v[40:41]
	v_pk_mul_f32 v[100:101], v[80:81], v[32:33]
	v_pk_fma_f32 v[98:99], v[82:83], v[42:43], v[98:99]
	v_pk_fma_f32 v[100:101], v[82:83], v[34:35], v[100:101]
	v_pk_fma_f32 v[98:99], v[84:85], v[44:45], v[98:99]
	v_pk_fma_f32 v[100:101], v[84:85], v[36:37], v[100:101]
	v_pk_fma_f32 v[98:99], v[86:87], v[46:47], v[98:99]
	v_pk_fma_f32 v[100:101], v[86:87], v[38:39], v[100:101]
	v_add_f32_e32 v98, v98, v99
	v_add_f32_e32 v100, v100, v101
	ds_read_b128 v[0:3], v97 offset:3072
	ds_read_b128 v[4:7], v97 offset:3088
	v_add_f32_dpp v98, v98, v98 quad_perm:[1,0,3,2] row_mask:0xf bank_mask:0xf bound_ctrl:1
	v_add_f32_dpp v100, v100, v100 quad_perm:[1,0,3,2] row_mask:0xf bank_mask:0xf bound_ctrl:1
	ds_read_b128 v[8:11], v97 offset:3328
	ds_read_b128 v[12:15], v97 offset:3344
	v_add_f32_dpp v98, v98, v98 quad_perm:[2,3,0,1] row_mask:0xf bank_mask:0xf bound_ctrl:1
	v_add_f32_dpp v100, v100, v100 quad_perm:[2,3,0,1] row_mask:0xf bank_mask:0xf bound_ctrl:1
	ds_read_b128 v[24:27], v97 offset:3840
	ds_read_b128 v[28:31], v97 offset:3856
	v_add_f32_dpp v98, v98, v98 row_half_mirror row_mask:0xf bank_mask:0xf bound_ctrl:1
	v_add_f32_dpp v100, v100, v100 row_half_mirror row_mask:0xf bank_mask:0xf bound_ctrl:1
	ds_read_b32 v88, v102 offset:4352
	ds_read_b128 v[16:19], v97 offset:3584
	ds_read_b128 v[20:23], v97 offset:3600
	ds_read_b128 v[32:35], v97 offset:4096
	ds_read_b128 v[36:39], v97 offset:4112
	ds_write_b32 v89, v100 offset:0
	s_waitcnt lgkmcnt(11)
	v_pk_mul_f32 v[80:81], v[80:81], v[48:49]
	v_pk_mul_f32 v[82:83], v[82:83], v[50:51]
	v_pk_mul_f32 v[84:85], v[84:85], v[52:53]
	v_pk_mul_f32 v[86:87], v[86:87], v[54:55]
	v_pk_fma_f32 v[80:81], v[90:91], v[64:65], v[80:81] op_sel_hi:[0,1,1]
	v_pk_fma_f32 v[82:83], v[90:91], v[66:67], v[82:83] op_sel_hi:[0,1,1]
	v_pk_fma_f32 v[84:85], v[90:91], v[68:69], v[84:85] op_sel_hi:[0,1,1]
	v_pk_fma_f32 v[86:87], v[90:91], v[70:71], v[86:87] op_sel_hi:[0,1,1]
	v_pk_fma_f32 v[80:81], v[98:99], v[56:57], v[80:81] op_sel_hi:[0,1,1]
	v_pk_fma_f32 v[82:83], v[98:99], v[58:59], v[82:83] op_sel_hi:[0,1,1]
	v_pk_fma_f32 v[84:85], v[98:99], v[60:61], v[84:85] op_sel_hi:[0,1,1]
	v_pk_fma_f32 v[86:87], v[98:99], v[62:63], v[86:87] op_sel_hi:[0,1,1]
	s_waitcnt lgkmcnt(9)
	v_pk_mul_f32 v[98:99], v[80:81], v[0:1]
	v_pk_mul_f32 v[100:101], v[80:81], v[72:73]
	v_pk_fma_f32 v[98:99], v[82:83], v[2:3], v[98:99]
	v_pk_fma_f32 v[100:101], v[82:83], v[74:75], v[100:101]
	v_pk_fma_f32 v[98:99], v[84:85], v[4:5], v[98:99]
	v_pk_fma_f32 v[100:101], v[84:85], v[76:77], v[100:101]
	v_pk_fma_f32 v[98:99], v[86:87], v[6:7], v[98:99]
	v_pk_fma_f32 v[100:101], v[86:87], v[78:79], v[100:101]
	v_add_f32_e32 v98, v98, v99
	v_add_f32_e32 v100, v100, v101
	ds_read_b128 v[40:43], v97 offset:4608
	ds_read_b128 v[44:47], v97 offset:4624
	v_add_f32_dpp v98, v98, v98 quad_perm:[1,0,3,2] row_mask:0xf bank_mask:0xf bound_ctrl:1
	v_add_f32_dpp v100, v100, v100 quad_perm:[1,0,3,2] row_mask:0xf bank_mask:0xf bound_ctrl:1
	ds_read_b128 v[48:51], v97 offset:4864
	ds_read_b128 v[52:55], v97 offset:4880
	v_add_f32_dpp v98, v98, v98 quad_perm:[2,3,0,1] row_mask:0xf bank_mask:0xf bound_ctrl:1
	v_add_f32_dpp v100, v100, v100 quad_perm:[2,3,0,1] row_mask:0xf bank_mask:0xf bound_ctrl:1
	ds_read_b128 v[64:67], v97 offset:5376
	ds_read_b128 v[68:71], v97 offset:5392
	v_add_f32_dpp v98, v98, v98 row_half_mirror row_mask:0xf bank_mask:0xf bound_ctrl:1
	v_add_f32_dpp v100, v100, v100 row_half_mirror row_mask:0xf bank_mask:0xf bound_ctrl:1
	ds_read_b32 v90, v102 offset:5888
	ds_read_b128 v[56:59], v97 offset:5120
	ds_read_b128 v[60:63], v97 offset:5136
	ds_read_b128 v[72:75], v97 offset:5632
	ds_read_b128 v[76:79], v97 offset:5648
	ds_write_b32 v89, v100 offset:128
	s_waitcnt lgkmcnt(11)
	v_pk_mul_f32 v[80:81], v[80:81], v[8:9]
	v_pk_mul_f32 v[82:83], v[82:83], v[10:11]
	v_pk_mul_f32 v[84:85], v[84:85], v[12:13]
	v_pk_mul_f32 v[86:87], v[86:87], v[14:15]
	v_pk_fma_f32 v[80:81], v[88:89], v[24:25], v[80:81] op_sel_hi:[0,1,1]
	v_pk_fma_f32 v[82:83], v[88:89], v[26:27], v[82:83] op_sel_hi:[0,1,1]
	v_pk_fma_f32 v[84:85], v[88:89], v[28:29], v[84:85] op_sel_hi:[0,1,1]
	v_pk_fma_f32 v[86:87], v[88:89], v[30:31], v[86:87] op_sel_hi:[0,1,1]
	v_pk_fma_f32 v[80:81], v[98:99], v[16:17], v[80:81] op_sel_hi:[0,1,1]
	v_pk_fma_f32 v[82:83], v[98:99], v[18:19], v[82:83] op_sel_hi:[0,1,1]
	v_pk_fma_f32 v[84:85], v[98:99], v[20:21], v[84:85] op_sel_hi:[0,1,1]
	v_pk_fma_f32 v[86:87], v[98:99], v[22:23], v[86:87] op_sel_hi:[0,1,1]
	s_waitcnt lgkmcnt(9)
	v_pk_mul_f32 v[98:99], v[80:81], v[40:41]
	v_pk_mul_f32 v[100:101], v[80:81], v[32:33]
	v_pk_fma_f32 v[98:99], v[82:83], v[42:43], v[98:99]
	v_pk_fma_f32 v[100:101], v[82:83], v[34:35], v[100:101]
	v_pk_fma_f32 v[98:99], v[84:85], v[44:45], v[98:99]
	v_pk_fma_f32 v[100:101], v[84:85], v[36:37], v[100:101]
	v_pk_fma_f32 v[98:99], v[86:87], v[46:47], v[98:99]
	v_pk_fma_f32 v[100:101], v[86:87], v[38:39], v[100:101]
	v_add_f32_e32 v98, v98, v99
	v_add_f32_e32 v100, v100, v101
	ds_read_b128 v[0:3], v97 offset:6144
	ds_read_b128 v[4:7], v97 offset:6160
	v_add_f32_dpp v98, v98, v98 quad_perm:[1,0,3,2] row_mask:0xf bank_mask:0xf bound_ctrl:1
	v_add_f32_dpp v100, v100, v100 quad_perm:[1,0,3,2] row_mask:0xf bank_mask:0xf bound_ctrl:1
	ds_read_b128 v[8:11], v97 offset:6400
	ds_read_b128 v[12:15], v97 offset:6416
	v_add_f32_dpp v98, v98, v98 quad_perm:[2,3,0,1] row_mask:0xf bank_mask:0xf bound_ctrl:1
	v_add_f32_dpp v100, v100, v100 quad_perm:[2,3,0,1] row_mask:0xf bank_mask:0xf bound_ctrl:1
	ds_read_b128 v[24:27], v97 offset:6912
	ds_read_b128 v[28:31], v97 offset:6928
	v_add_f32_dpp v98, v98, v98 row_half_mirror row_mask:0xf bank_mask:0xf bound_ctrl:1
	v_add_f32_dpp v100, v100, v100 row_half_mirror row_mask:0xf bank_mask:0xf bound_ctrl:1
	ds_read_b32 v88, v102 offset:7424
	ds_read_b128 v[16:19], v97 offset:6656
	ds_read_b128 v[20:23], v97 offset:6672
	ds_read_b128 v[32:35], v97 offset:7168
	ds_read_b128 v[36:39], v97 offset:7184
	ds_write_b32 v89, v100 offset:256
	s_waitcnt lgkmcnt(11)
	v_pk_mul_f32 v[80:81], v[80:81], v[48:49]
	v_pk_mul_f32 v[82:83], v[82:83], v[50:51]
	v_pk_mul_f32 v[84:85], v[84:85], v[52:53]
	v_pk_mul_f32 v[86:87], v[86:87], v[54:55]
	v_pk_fma_f32 v[80:81], v[90:91], v[64:65], v[80:81] op_sel_hi:[0,1,1]
	v_pk_fma_f32 v[82:83], v[90:91], v[66:67], v[82:83] op_sel_hi:[0,1,1]
	v_pk_fma_f32 v[84:85], v[90:91], v[68:69], v[84:85] op_sel_hi:[0,1,1]
	v_pk_fma_f32 v[86:87], v[90:91], v[70:71], v[86:87] op_sel_hi:[0,1,1]
	v_pk_fma_f32 v[80:81], v[98:99], v[56:57], v[80:81] op_sel_hi:[0,1,1]
	v_pk_fma_f32 v[82:83], v[98:99], v[58:59], v[82:83] op_sel_hi:[0,1,1]
	v_pk_fma_f32 v[84:85], v[98:99], v[60:61], v[84:85] op_sel_hi:[0,1,1]
	v_pk_fma_f32 v[86:87], v[98:99], v[62:63], v[86:87] op_sel_hi:[0,1,1]
	s_waitcnt lgkmcnt(9)
	v_pk_mul_f32 v[98:99], v[80:81], v[0:1]
	v_pk_mul_f32 v[100:101], v[80:81], v[72:73]
	v_pk_fma_f32 v[98:99], v[82:83], v[2:3], v[98:99]
	v_pk_fma_f32 v[100:101], v[82:83], v[74:75], v[100:101]
	v_pk_fma_f32 v[98:99], v[84:85], v[4:5], v[98:99]
	v_pk_fma_f32 v[100:101], v[84:85], v[76:77], v[100:101]
	v_pk_fma_f32 v[98:99], v[86:87], v[6:7], v[98:99]
	v_pk_fma_f32 v[100:101], v[86:87], v[78:79], v[100:101]
	v_add_f32_e32 v98, v98, v99
	v_add_f32_e32 v100, v100, v101
	ds_read_b128 v[40:43], v97 offset:7680
	ds_read_b128 v[44:47], v97 offset:7696
	v_add_f32_dpp v98, v98, v98 quad_perm:[1,0,3,2] row_mask:0xf bank_mask:0xf bound_ctrl:1
	v_add_f32_dpp v100, v100, v100 quad_perm:[1,0,3,2] row_mask:0xf bank_mask:0xf bound_ctrl:1
	ds_read_b128 v[48:51], v97 offset:7936
	ds_read_b128 v[52:55], v97 offset:7952
	v_add_f32_dpp v98, v98, v98 quad_perm:[2,3,0,1] row_mask:0xf bank_mask:0xf bound_ctrl:1
	v_add_f32_dpp v100, v100, v100 quad_perm:[2,3,0,1] row_mask:0xf bank_mask:0xf bound_ctrl:1
	ds_read_b128 v[64:67], v97 offset:8448
	ds_read_b128 v[68:71], v97 offset:8464
	v_add_f32_dpp v98, v98, v98 row_half_mirror row_mask:0xf bank_mask:0xf bound_ctrl:1
	v_add_f32_dpp v100, v100, v100 row_half_mirror row_mask:0xf bank_mask:0xf bound_ctrl:1
	ds_read_b32 v90, v102 offset:8960
	ds_read_b128 v[56:59], v97 offset:8192
	ds_read_b128 v[60:63], v97 offset:8208
	ds_read_b128 v[72:75], v97 offset:8704
	ds_read_b128 v[76:79], v97 offset:8720
	ds_write_b32 v89, v100 offset:384
	s_add_i32 s7, s7, -4
	v_add_u32_e32 v97, 0x1800, v97
	v_add_u32_e32 v102, 0x1800, v102
	v_add_u32_e32 v89, 0x200, v89
	s_cmp_eq_u32 s7, 0
	s_cbranch_scc0 .Lscnh_loop
	s_branch .LBB0_469
